# v20 + attention far-block body: softmax-0 accumulator init quad kept loop-invariant in v[252:255] as MFMA SrcC, softmax-1 init computed once per block (12 fewer VALU per half-block)
# baseline (speedup 1.0000x reference)
.LBB0_138:
	v_add_f32_e32 v0, v0, v54
	s_mov_b32 s6, 0xf800000
	v_mul_f32_e32 v2, 0x4f800000, v0
	v_cmp_gt_f32_e32 vcc, s6, v0
	s_waitcnt lgkmcnt(0)
	s_barrier
	v_cndmask_b32_e32 v0, v0, v2, vcc
	v_sqrt_f32_e32 v2, v0
	ds_read_b64 v[170:171], v1 offset:512
	s_lshl_b32 s41, s10, 1
	v_add_u32_e32 v3, -1, v2
	v_fma_f32 v53, -v3, v2, v0
	v_add_u32_e32 v52, 1, v2
	v_cmp_ge_f32_e64 s[44:45], 0, v53
	v_subrev_u32_e32 v209, 64, v207
	s_add_i32 s51, s41, 2
	v_cndmask_b32_e64 v3, v2, v3, s[44:45]
	v_fma_f32 v2, -v52, v2, v0
	v_cmp_lt_f32_e64 s[44:45], 0, v2
	v_add_u32_e32 v159, 0xffffff81, v163
	v_or_b32_e32 v161, 15, v163
	v_cndmask_b32_e64 v2, v3, v52, s[44:45]
	v_add_f32_e32 v52, v55, v56
	v_mul_f32_e32 v53, 0x4f800000, v52
	v_cmp_gt_f32_e64 s[44:45], s6, v52
	v_mul_f32_e32 v3, 0x37800000, v2
	v_cndmask_b32_e32 v2, v2, v3, vcc
	v_cndmask_b32_e64 v52, v52, v53, s[44:45]
	v_sqrt_f32_e32 v53, v52
	v_cmp_class_f32_e32 vcc, v0, v180
	v_subrev_u32_e32 v208, 49, v163
	v_add_u32_e32 v210, v209, v197
	v_cndmask_b32_e32 v0, v2, v0, vcc
	v_add_u32_e32 v2, -1, v53
	v_fma_f32 v3, -v2, v53, v52
	v_cmp_ge_f32_e32 vcc, 0, v3
	v_add_u32_e32 v3, 1, v53
	s_waitcnt lgkmcnt(0)
	v_fma_f32 v120, v192, v0, v171
	v_cndmask_b32_e32 v2, v53, v2, vcc
	v_fma_f32 v53, -v3, v53, v52
	v_cmp_lt_f32_e32 vcc, 0, v53
	v_mov_b32_e32 v0, v1
	v_add_u32_e32 v211, v145, v209
	v_cndmask_b32_e32 v2, v2, v3, vcc
	v_mul_f32_e32 v3, 0x37800000, v2
	v_cndmask_b32_e64 v2, v2, v3, s[44:45]
	v_cmp_class_f32_e32 vcc, v52, v180
	v_mov_b32_e32 v3, v1
	v_add_u32_e32 v212, v198, v209
	v_cndmask_b32_e32 v2, v2, v52, vcc
	v_fma_f32 v122, v192, v2, v171
	v_mov_b32_e32 v2, v1
	v_mov_b64_e32 v[106:107], v[2:3]
	v_mov_b64_e32 v[102:103], v[2:3]
	v_mov_b64_e32 v[90:91], v[2:3]
	v_mov_b64_e32 v[86:87], v[2:3]
	v_mov_b64_e32 v[74:75], v[2:3]
	v_mov_b64_e32 v[70:71], v[2:3]
	v_mov_b64_e32 v[58:59], v[2:3]
	v_mov_b64_e32 v[54:55], v[2:3]
	v_mov_b64_e32 v[114:115], v[2:3]
	v_mov_b64_e32 v[110:111], v[2:3]
	v_mov_b64_e32 v[98:99], v[2:3]
	v_mov_b64_e32 v[94:95], v[2:3]
	v_mov_b64_e32 v[82:83], v[2:3]
	v_mov_b64_e32 v[78:79], v[2:3]
	v_mov_b64_e32 v[66:67], v[2:3]
	v_mov_b64_e32 v[62:63], v[2:3]
	v_mov_b64_e32 v[118:119], v[2:3]
	v_mov_b64_e32 v[130:131], v[2:3]
	v_add_u32_e32 v213, v199, v209
	v_add_u32_e32 v214, v200, v209
	v_add_u32_e32 v215, v201, v209
	v_add_u32_e32 v216, v202, v209
	v_mov_b32_e32 v121, v120
	v_mov_b32_e32 v124, v120
	v_mov_b32_e32 v123, v120
	v_mov_b32_e32 v125, v122
	v_mov_b32_e32 v126, v122
	v_mov_b32_e32 v127, v122
	v_sub_f32_e32 v252, v170, v120
	v_sub_f32_e32 v253, v170, v121
	v_sub_f32_e32 v254, v170, v124
	v_sub_f32_e32 v255, v170, v123
	s_mov_b32 s57, 0
	v_mov_b64_e32 v[104:105], v[0:1]
	v_mov_b64_e32 v[100:101], v[0:1]
	v_mov_b64_e32 v[88:89], v[0:1]
	v_mov_b64_e32 v[84:85], v[0:1]
	v_mov_b64_e32 v[72:73], v[0:1]
	v_mov_b64_e32 v[68:69], v[0:1]
	v_mov_b64_e32 v[56:57], v[0:1]
	v_mov_b64_e32 v[52:53], v[0:1]
	v_mov_b64_e32 v[112:113], v[0:1]
	v_mov_b64_e32 v[108:109], v[0:1]
	v_mov_b64_e32 v[96:97], v[0:1]
	v_mov_b64_e32 v[92:93], v[0:1]
	v_mov_b64_e32 v[80:81], v[0:1]
	v_mov_b64_e32 v[76:77], v[0:1]
	v_mov_b64_e32 v[64:65], v[0:1]
	v_mov_b64_e32 v[60:61], v[0:1]
	v_mov_b64_e32 v[116:117], v[0:1]
	v_mov_b64_e32 v[128:129], v[0:1]
	s_branch .LBB0_140

.Lfar_a:
	s_or_b64 exec, exec, s[12:13]
	s_lshl_b32 s13, s29, 6
	s_mul_i32 s12, s29, 0x2200
	s_add_i32 s13, s13, 0
	v_add_u32_e32 v171, s12, v139
	ds_read_b128 v[222:225], v171 offset:1024
	ds_read_b128 v[226:229], v171 offset:1088
	ds_read_b128 v[230:233], v171 offset:2112
	ds_read_b128 v[234:237], v171 offset:2176
	s_waitcnt lgkmcnt(4)
	s_waitcnt lgkmcnt(3)
	v_mfma_f32_16x16x32_bf16 v[222:225], v[222:225], v[4:7], v[252:255]
	s_waitcnt lgkmcnt(1)
	v_mfma_f32_16x16x32_bf16 v[230:233], v[230:233], v[4:7], v[252:255]
	v_mfma_f32_16x16x32_bf16 v[222:225], v[226:229], v[8:11], v[222:225]
	ds_read_b128 v[226:229], v171 offset:1152
	ds_read_b128 v[238:241], v171 offset:1216
	s_waitcnt lgkmcnt(2)
	v_mfma_f32_16x16x32_bf16 v[230:233], v[234:237], v[8:11], v[230:233]
	ds_read_b128 v[234:237], v171 offset:2240
	ds_read_b128 v[242:245], v171 offset:2304
	v_sub_f32_e32 v249, v173, v127
	v_sub_f32_e32 v248, v172, v126
	v_sub_f32_e32 v247, v3, v125
	v_sub_f32_e32 v246, v2, v122
	v_exp_f32_e32 v3, v223
	v_exp_f32_e32 v219, v225
	s_waitcnt lgkmcnt(3)
	v_mfma_f32_16x16x32_bf16 v[226:229], v[226:229], v[12:15], v[246:249]
	v_exp_f32_e32 v225, v231
	s_nop 1
	s_waitcnt lgkmcnt(2)
	v_mfma_f32_16x16x32_bf16 v[226:229], v[238:241], v[16:19], v[226:229]
	v_add3_u32 v0, s13, v134, v135
	v_exp_f32_e32 v217, v224
	s_waitcnt lgkmcnt(1)
	v_mfma_f32_16x16x32_bf16 v[172:175], v[234:237], v[12:15], v[246:249]
	ds_read_b128 v[234:237], v0 offset:18432
	ds_read_b128 v[238:241], v0 offset:20736
	s_nop 1
	v_exp_f32_e32 v2, v226
	v_exp_f32_e32 v171, v227
	s_waitcnt lgkmcnt(2)
	v_mfma_f32_16x16x32_bf16 v[172:175], v[242:245], v[16:19], v[172:175]
	ds_read_b128 v[242:245], v0 offset:23040
	ds_read_b128 v[246:249], v0 offset:25344
	v_exp_f32_e32 v0, v222
	v_exp_f32_e32 v218, v228
	v_exp_f32_e32 v223, v229
	v_exp_f32_e32 v222, v230
	s_nop 1
	v_exp_f32_e32 v224, v172
	v_exp_f32_e32 v226, v173
	v_exp_f32_e32 v227, v232
	v_exp_f32_e32 v228, v174
	v_exp_f32_e32 v229, v233
	v_exp_f32_e32 v230, v175
	v_cvt_pk_bf16_f32 v172, v0, v3
	v_cvt_pk_bf16_f32 v173, v217, v219
	v_cvt_pk_bf16_f32 v174, v222, v225
	v_cvt_pk_bf16_f32 v175, v227, v229
	v_cvt_pk_bf16_f32 v222, v2, v171
	v_cvt_pk_bf16_f32 v223, v218, v223
	v_cvt_pk_bf16_f32 v224, v224, v226
	v_cvt_pk_bf16_f32 v225, v228, v230
	v_add3_u32 v0, s13, v135, v134
	s_waitcnt lgkmcnt(3)
	v_mfma_f32_16x16x32_bf16 v[104:107], v[234:237], v[172:175], v[104:107]
	ds_read_b128 v[226:229], v0 offset:27648
	ds_read_b128 v[230:233], v0 offset:29952
	v_mfma_f32_16x16x32_bf16 v[112:115], v[234:237], v[222:225], v[112:115]
	ds_read_b128 v[234:237], v0 offset:32256
	s_waitcnt lgkmcnt(5)
	v_mfma_f32_16x16x32_bf16 v[100:103], v[238:241], v[172:175], v[100:103]
	v_mfma_f32_16x16x32_bf16 v[108:111], v[238:241], v[222:225], v[108:111]
	ds_read_b128 v[238:241], v0 offset:34560
	s_waitcnt lgkmcnt(5)
	v_mfma_f32_16x16x32_bf16 v[88:91], v[242:245], v[172:175], v[88:91]
	v_mfma_f32_16x16x32_bf16 v[96:99], v[242:245], v[222:225], v[96:99]
	s_waitcnt lgkmcnt(4)
	v_mfma_f32_16x16x32_bf16 v[84:87], v[246:249], v[172:175], v[84:87]
	v_mfma_f32_16x16x32_bf16 v[92:95], v[246:249], v[222:225], v[92:95]
	s_mov_b32 s66, s64
	s_mov_b32 s67, s64
	s_waitcnt lgkmcnt(3)
	v_mfma_f32_16x16x32_bf16 v[72:75], v[226:229], v[172:175], v[72:75]
	s_mov_b32 s65, s64
	v_mfma_f32_16x16x32_bf16 v[80:83], v[226:229], v[222:225], v[80:83]
	v_mov_b64_e32 v[228:229], s[66:67]
	v_mov_b64_e32 v[226:227], s[64:65]
	s_waitcnt lgkmcnt(2)
	v_mfma_f32_16x16x32_bf16 v[68:71], v[230:233], v[172:175], v[68:71]
	v_mfma_f32_16x16x32_bf16 v[76:79], v[230:233], v[222:225], v[76:79]
	s_waitcnt lgkmcnt(1)
	v_mfma_f32_16x16x32_bf16 v[56:59], v[234:237], v[172:175], v[56:59]
	v_mfma_f32_16x16x32_bf16 v[64:67], v[234:237], v[222:225], v[64:67]
	s_waitcnt lgkmcnt(0)
	v_mfma_f32_16x16x32_bf16 v[52:55], v[238:241], v[172:175], v[52:55]
	v_mfma_f32_16x16x32_bf16 v[60:63], v[238:241], v[222:225], v[60:63]
	v_mfma_f32_16x16x32_bf16 v[128:131], v[226:229], v[172:175], v[128:131]
	v_mfma_f32_16x16x32_bf16 v[116:119], v[226:229], v[222:225], v[116:119]
	s_branch .LBB0_142

.LBB0_162:
	s_andn2_saveexec_b64 s[12:13], s[12:13]
	s_cbranch_execz .LBB0_141
	s_waitcnt lgkmcnt(0)
	v_mov_b32_e32 v0, v170
	v_mov_b32_e32 v217, v170
	s_cmp_eq_u64 s[12:13], 0
	s_cbranch_scc1 .Lfar_a
	s_branch .LBB0_141

.Lfar_b:
	s_or_b64 exec, exec, s[12:13]
	s_lshl_b32 s13, s29, 6
	s_mul_i32 s12, s29, 0x2200
	s_add_i32 s13, s13, 0
	v_add_u32_e32 v171, s12, v139
	ds_read_b128 v[222:225], v171 offset:36864
	ds_read_b128 v[226:229], v171 offset:36928
	ds_read_b128 v[230:233], v171 offset:37952
	ds_read_b128 v[234:237], v171 offset:38016
	s_waitcnt lgkmcnt(4)
	s_waitcnt lgkmcnt(3)
	v_mfma_f32_16x16x32_bf16 v[222:225], v[222:225], v[4:7], v[252:255]
	s_waitcnt lgkmcnt(1)
	v_mfma_f32_16x16x32_bf16 v[230:233], v[230:233], v[4:7], v[252:255]
	v_mfma_f32_16x16x32_bf16 v[222:225], v[226:229], v[8:11], v[222:225]
	ds_read_b128 v[226:229], v171 offset:36992
	ds_read_b128 v[238:241], v171 offset:37056
	s_waitcnt lgkmcnt(2)
	v_mfma_f32_16x16x32_bf16 v[230:233], v[234:237], v[8:11], v[230:233]
	ds_read_b128 v[234:237], v171 offset:38080
	ds_read_b128 v[242:245], v171 offset:38144
	v_sub_f32_e32 v249, v173, v127
	v_sub_f32_e32 v248, v172, v126
	v_sub_f32_e32 v247, v3, v125
	v_sub_f32_e32 v246, v2, v122
	v_exp_f32_e32 v3, v223
	v_exp_f32_e32 v219, v225
	s_waitcnt lgkmcnt(3)
	v_mfma_f32_16x16x32_bf16 v[226:229], v[226:229], v[12:15], v[246:249]
	v_exp_f32_e32 v225, v231
	s_nop 1
	s_waitcnt lgkmcnt(2)
	v_mfma_f32_16x16x32_bf16 v[226:229], v[238:241], v[16:19], v[226:229]
	v_add3_u32 v0, s13, v134, v135
	v_exp_f32_e32 v217, v224
	s_waitcnt lgkmcnt(1)
	v_mfma_f32_16x16x32_bf16 v[172:175], v[234:237], v[12:15], v[246:249]
	ds_read_b128 v[234:237], v0 offset:54272
	ds_read_b128 v[238:241], v0 offset:56576
	s_nop 1
	v_exp_f32_e32 v2, v226
	v_exp_f32_e32 v171, v227
	s_waitcnt lgkmcnt(2)
	v_mfma_f32_16x16x32_bf16 v[172:175], v[242:245], v[16:19], v[172:175]
	ds_read_b128 v[242:245], v0 offset:58880
	ds_read_b128 v[246:249], v0 offset:61184
	v_exp_f32_e32 v0, v222
	v_exp_f32_e32 v218, v228
	v_exp_f32_e32 v223, v229
	v_exp_f32_e32 v222, v230
	s_nop 1
	v_exp_f32_e32 v224, v172
	v_exp_f32_e32 v226, v173
	v_exp_f32_e32 v227, v232
	v_exp_f32_e32 v228, v174
	v_exp_f32_e32 v229, v233
	v_exp_f32_e32 v230, v175
	v_cvt_pk_bf16_f32 v172, v0, v3
	v_cvt_pk_bf16_f32 v173, v217, v219
	v_cvt_pk_bf16_f32 v174, v222, v225
	v_cvt_pk_bf16_f32 v175, v227, v229
	v_cvt_pk_bf16_f32 v222, v2, v171
	v_cvt_pk_bf16_f32 v223, v218, v223
	v_cvt_pk_bf16_f32 v224, v224, v226
	v_cvt_pk_bf16_f32 v225, v228, v230
	v_add3_u32 v0, s13, v135, v134
	v_add_u32_e32 v2, 0x10100, v0
	ds_read_b128 v[226:229], v0 offset:63488
	ds_read_b128 v[230:233], v2
	v_add_u32_e32 v2, 0x10a00, v0
	v_add_u32_e32 v0, 0x11300, v0
	s_waitcnt lgkmcnt(5)
	v_mfma_f32_16x16x32_bf16 v[104:107], v[234:237], v[172:175], v[104:107]
	v_mfma_f32_16x16x32_bf16 v[112:115], v[234:237], v[222:225], v[112:115]
	ds_read_b128 v[234:237], v2
	s_waitcnt lgkmcnt(5)
	v_mfma_f32_16x16x32_bf16 v[100:103], v[238:241], v[172:175], v[100:103]
	v_mfma_f32_16x16x32_bf16 v[108:111], v[238:241], v[222:225], v[108:111]
	ds_read_b128 v[238:241], v0
	s_waitcnt lgkmcnt(5)
	v_mfma_f32_16x16x32_bf16 v[88:91], v[242:245], v[172:175], v[88:91]
	v_mfma_f32_16x16x32_bf16 v[96:99], v[242:245], v[222:225], v[96:99]
	s_waitcnt lgkmcnt(4)
	v_mfma_f32_16x16x32_bf16 v[84:87], v[246:249], v[172:175], v[84:87]
	v_mfma_f32_16x16x32_bf16 v[92:95], v[246:249], v[222:225], v[92:95]
	s_mov_b32 s66, s64
	s_mov_b32 s67, s64
	s_waitcnt lgkmcnt(3)
	v_mfma_f32_16x16x32_bf16 v[72:75], v[226:229], v[172:175], v[72:75]
	s_mov_b32 s65, s64
	v_mfma_f32_16x16x32_bf16 v[80:83], v[226:229], v[222:225], v[80:83]
	v_mov_b64_e32 v[228:229], s[66:67]
	v_mov_b64_e32 v[226:227], s[64:65]
	s_waitcnt lgkmcnt(2)
	v_mfma_f32_16x16x32_bf16 v[68:71], v[230:233], v[172:175], v[68:71]
	v_mfma_f32_16x16x32_bf16 v[76:79], v[230:233], v[222:225], v[76:79]
	s_waitcnt lgkmcnt(1)
	v_mfma_f32_16x16x32_bf16 v[56:59], v[234:237], v[172:175], v[56:59]
	v_mfma_f32_16x16x32_bf16 v[64:67], v[234:237], v[222:225], v[64:67]
	s_waitcnt lgkmcnt(0)
	v_mfma_f32_16x16x32_bf16 v[52:55], v[238:241], v[172:175], v[52:55]
	v_mfma_f32_16x16x32_bf16 v[60:63], v[238:241], v[222:225], v[60:63]
	v_mfma_f32_16x16x32_bf16 v[128:131], v[226:229], v[172:175], v[128:131]
	v_mfma_f32_16x16x32_bf16 v[116:119], v[226:229], v[222:225], v[116:119]
	s_branch .LBB0_168

	.amdhsa_kernel _Z9yoco_mega6Params
		.amdhsa_group_segment_fixed_size 0
		.amdhsa_private_segment_fixed_size 0
		.amdhsa_kernarg_size 560
		.amdhsa_user_sgpr_count 2
		.amdhsa_user_sgpr_dispatch_ptr 0
		.amdhsa_user_sgpr_queue_ptr 0
		.amdhsa_user_sgpr_kernarg_segment_ptr 1
		.amdhsa_user_sgpr_dispatch_id 0
		.amdhsa_user_sgpr_kernarg_preload_length 0
		.amdhsa_user_sgpr_kernarg_preload_offset 0
		.amdhsa_user_sgpr_private_segment_size 0
		.amdhsa_uses_dynamic_stack 0
		.amdhsa_enable_private_segment 0
		.amdhsa_system_sgpr_workgroup_id_x 1
		.amdhsa_system_sgpr_workgroup_id_y 0
		.amdhsa_system_sgpr_workgroup_id_z 0
		.amdhsa_system_sgpr_workgroup_info 0
		.amdhsa_system_vgpr_workitem_id 2
		.amdhsa_next_free_vgpr 256
		.amdhsa_next_free_sgpr 102
		.amdhsa_accum_offset 256
		.amdhsa_reserve_vcc 1
		.amdhsa_float_round_mode_32 0
		.amdhsa_float_round_mode_16_64 0
		.amdhsa_float_denorm_mode_32 3
		.amdhsa_float_denorm_mode_16_64 3
		.amdhsa_dx10_clamp 1
		.amdhsa_ieee_mode 1
		.amdhsa_fp16_overflow 0
		.amdhsa_tg_split 0
		.amdhsa_exception_fp_ieee_invalid_op 0
		.amdhsa_exception_fp_denorm_src 0
		.amdhsa_exception_fp_ieee_div_zero 0
		.amdhsa_exception_fp_ieee_overflow 0
		.amdhsa_exception_fp_ieee_underflow 0
		.amdhsa_exception_fp_ieee_inexact 0
		.amdhsa_exception_int_div_zero 0
	.end_amdhsa_kernel

amdhsa.kernels:
  - .agpr_count:     0
    .args:
      - .offset:         0
        .size:           304
        .value_kind:     by_value
      - .offset:         304
        .size:           4
        .value_kind:     hidden_block_count_x
      - .offset:         308
        .size:           4
        .value_kind:     hidden_block_count_y
      - .offset:         312
        .size:           4
        .value_kind:     hidden_block_count_z
      - .offset:         316
        .size:           2
        .value_kind:     hidden_group_size_x
      - .offset:         318
        .size:           2
        .value_kind:     hidden_group_size_y
      - .offset:         320
        .size:           2
        .value_kind:     hidden_group_size_z
      - .offset:         322
        .size:           2
        .value_kind:     hidden_remainder_x
      - .offset:         324
        .size:           2
        .value_kind:     hidden_remainder_y
      - .offset:         326
        .size:           2
        .value_kind:     hidden_remainder_z
      - .offset:         344
        .size:           8
        .value_kind:     hidden_global_offset_x
      - .offset:         352
        .size:           8
        .value_kind:     hidden_global_offset_y
      - .offset:         360
        .size:           8
        .value_kind:     hidden_global_offset_z
      - .offset:         368
        .size:           2
        .value_kind:     hidden_grid_dims
      - .offset:         392
        .size:           8
        .value_kind:     hidden_multigrid_sync_arg
      - .offset:         424
        .size:           4
        .value_kind:     hidden_dynamic_lds_size
    .group_segment_fixed_size: 0
    .kernarg_segment_align: 8
    .kernarg_segment_size: 560
    .language:       OpenCL C
    .language_version:
      - 2
      - 0
    .max_flat_workgroup_size: 512
    .name:           _Z9yoco_mega6Params
    .private_segment_fixed_size: 0
    .sgpr_count:     108
    .sgpr_spill_count: 127
    .symbol:         _Z9yoco_mega6Params.kd
    .uniform_work_group_size: 1
    .uses_dynamic_stack: false
    .vgpr_count:     256
    .vgpr_spill_count: 0
    .wavefront_size: 64
